# P6 late entry 16us, P7 late entry 32us for odd WGs
# baseline (speedup 1.0000x reference)
;     __device__ void init(int M, int N, int G_, int c_, unsigned long long mask_ = 0ull) { nM = M / BM; nN = mask_ ? __builtin_popcountll(mask_) : N / BM; nwg = nM * nN; G = G_; c = c_; mask = mask_; }
; #define LAUNDER() do { tid = threadIdx.x; asm volatile("" : "+v"(tid)); lane = tid & 63; wid = __builtin_amdgcn_readfirstlane(tid >> 6); bx = blockIdx.x; asm volatile("" : "+s"(bx)); \
;         vcu = (G % 8 == 0) ? (bx % 8) * (G / 8) + bx / 8 : bx; gw = vcu * 8 + wid; ws = P.ws; asm volatile("" : "+s"(ws)); Q.ws = ws; XB = (bf16_t*)(ws + WS_XB); } while (0)
; __global__ void __launch_bounds__(512, 2) trunk_fwd(Params P) {
;     ...
;         LAUNDER();
;         if (PH(12)) {   pg8::Gemm g{(const bf16_t*)(ws + WS_PB), (const bf16_t*)(ws + WS_WPLE), T, DM, PLE}; pg8::StaticOrder S; S.init(T, DM, G, bx);
;             Epi<EPI_MRG_A> E{}; E.O = (bf16_t*)(ws + WS_GP); E.ldc = DM;
;             pg8::gemm_phase(lds, g, S, E); }
.LBB0_672:
	s_or_b64 exec, exec, s[2:3]
	v_mov_b32_e32 v194, v160
	v_writelane_b32 v255, s13, 3
	s_waitcnt lgkmcnt(0)
	s_barrier
	v_readlane_b32 s30, v252, 50
	v_readfirstlane_b32 s0, v194
	s_nop 3
	s_bitcmp1_b32 s30, 0
	s_cbranch_scc0 .Lstagger_p7_done
	s_sleep 127
	s_sleep 127
	s_sleep 127
	s_sleep 127
	s_sleep 127
	s_sleep 127
	s_sleep 127
	s_sleep 127
